# FFN up GEMM: RMSNorm row scales loaded at tile start (idle registers) so the epilogue has no load round trip and no vmcnt(0) behind the next tile's LDS-DMA prefetch
# speedup vs baseline: 1.0010x; 1.0010x over previous
; #define EGAS __attribute__((address_space(1)))
;     __host__ __device__ bool next(int i, Unit& u) const {
;         const long L = (long)i * G + c; if (L >= nwg) return false;
;         int wgid = (int)L; { const int q = nwg / NXCD, r = nwg % NXCD, xcd = wgid % NXCD, off = wgid / NXCD; wgid = (xcd < r ? xcd * (q + 1) : r * (q + 1) + (xcd - r) * q) + off; }
;         const int nig = WGM * nN, gid = wgid / nig, fm = gid * WGM, gsz = (nM - fm) < WGM ? (nM - fm) : WGM;
;         u.pm = fm + ((wgid % nig) % gsz); u.pn = (wgid % nig) / gsz; return true;
;     }
;     __device__ __forceinline__ void operator()(const f32x4 (&acc)[2][2][4][2], const Unit& u, int wr, int wc, int fr, int fq) const {
;     ...
;         if constexpr (MODE == EP_IN || MODE == EP_U) {
;             const EGAS float* rsp = WSF(WS_RSTD) + row0;
; #pragma unroll
;             for (int ai = 0; ai < 2; ++ai)
; #pragma unroll
;                 for (int m = 0; m < 4; ++m) rs[ai][m] = rsp[ai * HALF + m * 16];
;         }
; template <class Epi, class Sched, bool ALIGN_EPI = false, bool SP2 = false>
; __device__ __forceinline__ void gemm_phase(PG8_LAS unsigned char* lds, const Gemm g, const Sched& S, const Epi& E) {
;     ...
;         const bool has_next = S.next(ui + 1, nxt);
;         const char* nA = has_next ? (const char*)g.A + (size_t)nxt.pm * tstep : cA; const char* nB = has_next ? (const char*)g.Bt + (size_t)nxt.pn * tstep : cB;
.LBB0_1731:
	v_lshl_add_u32 v252, s22, 8, v145
	v_ashrrev_i32_e32 v253, 31, v252
	v_lshl_add_u64 v[252:253], v[252:253], 2, s[10:11]
	global_load_dword v166, v[252:253], off
	global_load_dword v167, v[252:253], off offset:64
	global_load_dword v168, v[252:253], off offset:128
	global_load_dword v169, v[252:253], off offset:192
	global_load_dword v170, v[252:253], off offset:512
	global_load_dword v171, v[252:253], off offset:576
	global_load_dword v172, v[252:253], off offset:640
	global_load_dword v173, v[252:253], off offset:704
	s_add_i32 s49, s49, 1
	s_mul_i32 s15, s49, s47
	s_mul_hi_u32 s17, s49, s2
	s_add_i32 s17, s17, s15
	s_mul_i32 s15, s49, s2
	s_add_u32 s18, s15, s3
	s_addc_u32 s19, s17, s36
	v_mov_b64_e32 v[2:3], 0xb00
	v_cmp_lt_i64_e64 s[40:41], s[18:19], v[2:3]
	v_mov_b64_e32 v[2:3], 0xaff
	v_cmp_gt_i64_e32 vcc, s[18:19], v[2:3]
	s_cbranch_vccnz .LBB0_1733
	s_ashr_i32 s14, s18, 31
	s_lshr_b32 s14, s14, 29
	s_add_i32 s14, s18, s14
	s_ashr_i32 s15, s14, 3
	s_and_b32 s14, s14, -8
	s_sub_i32 s14, s18, s14
	s_cmp_lt_i32 s14, 0
	s_movk_i32 s16, 0x161
	s_cselect_b32 s16, s16, 0x160
	s_mul_i32 s14, s14, s16
	s_add_i32 s14, s14, s15
	s_mul_hi_i32 s15, s14, 0x2e8ba2e9
	s_lshr_b32 s16, s15, 31
	s_ashr_i32 s15, s15, 5
	s_add_i32 s15, s15, s16
	s_lshl_b32 s16, s15, 2
	s_sub_i32 s17, 64, s16
	s_min_i32 s17, s17, 4
	s_abs_i32 s18, s17
	v_cvt_f32_u32_e32 v0, s18
	s_sub_i32 s20, 0, s18
	s_mulk_i32 s15, 0xb0
	s_sub_i32 s15, s14, s15
	v_rcp_iflag_f32_e32 v0, v0
	s_abs_i32 s14, s15
	s_xor_b32 s19, s15, s17
	s_ashr_i32 s19, s19, 31
	v_mul_f32_e32 v0, 0x4f7ffffe, v0
	v_cvt_u32_f32_e32 v0, v0
	s_nop 0
	v_readfirstlane_b32 s21, v0
	s_mul_i32 s20, s20, s21
	s_mul_hi_u32 s20, s21, s20
	s_add_i32 s21, s21, s20
	s_mul_hi_u32 s20, s14, s21
	s_mul_i32 s21, s20, s18
	s_sub_i32 s14, s14, s21
	s_add_i32 s28, s20, 1
	s_sub_i32 s21, s14, s18
	s_cmp_ge_u32 s14, s18
	s_cselect_b32 s20, s28, s20
	s_cselect_b32 s14, s21, s14
	s_add_i32 s21, s20, 1
	s_cmp_ge_u32 s14, s18
	s_cselect_b32 s14, s21, s20
	s_xor_b32 s14, s14, s19
	s_sub_i32 s14, s14, s19
	s_mul_i32 s17, s14, s17
	s_sub_i32 s15, s15, s17
	s_add_i32 s16, s16, s15

;     __device__ __forceinline__ void operator()(const f32x4 (&acc)[2][2][4][2], const Unit& u, int wr, int wc, int fr, int fq) const {
;     ...
; #pragma unroll
;         for (int ai = 0; ai < 2; ++ai)
; #pragma unroll
;             for (int m = 0; m < 4; ++m) {
;                 const unsigned row = (unsigned)(row0 + ai * HALF + m * 16);
; #pragma unroll
;                 for (int bj = 0; bj < 2; ++bj) {
;                     f32x4 v0 = acc[ai][bj][m][0], v1 = acc[ai][bj][m][1];
;                     if constexpr (MODE == EP_IN || MODE == EP_U) { v0 = v0 * rs[ai][m]; v1 = v1 * rs[ai][m]; }
;                     const int ct = bj * HALF + cw;
;     ...
;                         st8nt(WSB(WS_U) + row * 11264 + pn * 256 + ct, v0, v1);
.LBB0_1737:
	v_lshl_add_u32 v156, s22, 8, v145
	v_ashrrev_i32_e32 v157, 31, v156
	s_lshl_b32 s22, s23, 8
	s_movk_i32 s15, 0x2c00
	s_ashr_i32 s23, s22, 31
	v_mul_lo_u32 v0, v156, s15
	s_lshl_b64 s[22:23], s[22:23], 1
	v_mov_b32_e32 v143, v1
	s_andn2_b64 vcc, exec, s[40:41]
	v_pk_mul_f32 v[156:157], v[124:125], v[166:167] op_sel_hi:[1,0]
	v_pk_mul_f32 v[124:125], v[122:123], v[166:167] op_sel_hi:[1,0]
	v_lshl_add_u64 v[122:123], v[0:1], 1, s[8:9]
	v_lshl_add_u64 v[122:123], v[122:123], 0, s[22:23]
	v_pk_mul_f32 v[128:129], v[128:129], v[166:167] op_sel_hi:[1,0]
	v_pk_mul_f32 v[126:127], v[126:127], v[166:167] op_sel_hi:[1,0]
	v_lshl_add_u64 v[158:159], v[122:123], 0, v[142:143]
	v_cvt_pk_bf16_f32 v122, v126, v127
	v_cvt_pk_bf16_f32 v123, v128, v129
	v_cvt_pk_bf16_f32 v124, v124, v125
	v_cvt_pk_bf16_f32 v125, v156, v157
	global_store_dwordx4 v[158:159], v[122:125], off nt
	v_pk_mul_f32 v[120:121], v[120:121], v[166:167] op_sel_hi:[1,0]
	v_pk_mul_f32 v[118:119], v[118:119], v[166:167] op_sel_hi:[1,0]
	v_pk_mul_f32 v[122:123], v[116:117], v[166:167] op_sel_hi:[1,0]
	v_pk_mul_f32 v[116:117], v[114:115], v[166:167] op_sel_hi:[1,0]
	v_cvt_pk_bf16_f32 v114, v118, v119
	v_cvt_pk_bf16_f32 v115, v120, v121
	v_pk_mul_f32 v[112:113], v[112:113], v[166:167] op_sel:[0,1] op_sel_hi:[1,1]
	v_cvt_pk_bf16_f32 v116, v116, v117
	v_cvt_pk_bf16_f32 v117, v122, v123
	global_store_dwordx4 v[158:159], v[114:117], off offset:256 nt
	v_pk_mul_f32 v[110:111], v[110:111], v[166:167] op_sel:[0,1] op_sel_hi:[1,1]
	v_pk_mul_f32 v[104:105], v[104:105], v[166:167] op_sel:[0,1] op_sel_hi:[1,1]
	v_add_u32_e32 v114, 0x2c000, v0
	v_mov_b32_e32 v115, v1
	v_pk_mul_f32 v[116:117], v[108:109], v[166:167] op_sel:[0,1] op_sel_hi:[1,1]
	v_pk_mul_f32 v[108:109], v[106:107], v[166:167] op_sel:[0,1] op_sel_hi:[1,1]
	v_lshl_add_u64 v[106:107], v[114:115], 1, s[8:9]
	v_lshl_add_u64 v[106:107], v[106:107], 0, s[22:23]
	v_lshl_add_u64 v[114:115], v[106:107], 0, v[142:143]
	v_cvt_pk_bf16_f32 v106, v110, v111
	v_cvt_pk_bf16_f32 v107, v112, v113
	v_cvt_pk_bf16_f32 v108, v108, v109
	v_cvt_pk_bf16_f32 v109, v116, v117
	global_store_dwordx4 v[114:115], v[106:109], off nt
	v_pk_mul_f32 v[102:103], v[102:103], v[166:167] op_sel:[0,1] op_sel_hi:[1,1]
	v_pk_mul_f32 v[96:97], v[96:97], v[168:169] op_sel_hi:[1,0]
	v_pk_mul_f32 v[106:107], v[100:101], v[166:167] op_sel:[0,1] op_sel_hi:[1,1]
	v_pk_mul_f32 v[100:101], v[98:99], v[166:167] op_sel:[0,1] op_sel_hi:[1,1]
	v_cvt_pk_bf16_f32 v98, v102, v103
	v_cvt_pk_bf16_f32 v99, v104, v105
	v_pk_mul_f32 v[94:95], v[94:95], v[168:169] op_sel_hi:[1,0]
	v_cvt_pk_bf16_f32 v100, v100, v101
	v_cvt_pk_bf16_f32 v101, v106, v107
	global_store_dwordx4 v[114:115], v[98:101], off offset:256 nt
	v_pk_mul_f32 v[88:89], v[88:89], v[168:169] op_sel_hi:[1,0]
	v_pk_mul_f32 v[86:87], v[86:87], v[168:169] op_sel_hi:[1,0]
	v_add_u32_e32 v98, 0x58000, v0
	v_mov_b32_e32 v99, v1
	v_pk_mul_f32 v[100:101], v[92:93], v[168:169] op_sel_hi:[1,0]
	v_pk_mul_f32 v[92:93], v[90:91], v[168:169] op_sel_hi:[1,0]
	v_lshl_add_u64 v[90:91], v[98:99], 1, s[8:9]
	v_lshl_add_u64 v[90:91], v[90:91], 0, s[22:23]
	v_lshl_add_u64 v[98:99], v[90:91], 0, v[142:143]
	v_cvt_pk_bf16_f32 v90, v94, v95
	v_cvt_pk_bf16_f32 v91, v96, v97
	v_cvt_pk_bf16_f32 v92, v92, v93
	v_cvt_pk_bf16_f32 v93, v100, v101
	global_store_dwordx4 v[98:99], v[90:93], off nt
	v_pk_mul_f32 v[80:81], v[80:81], v[168:169] op_sel:[0,1] op_sel_hi:[1,1]
	v_pk_mul_f32 v[78:79], v[78:79], v[168:169] op_sel:[0,1] op_sel_hi:[1,1]
	v_pk_mul_f32 v[90:91], v[84:85], v[168:169] op_sel_hi:[1,0]
	v_pk_mul_f32 v[84:85], v[82:83], v[168:169] op_sel_hi:[1,0]
	v_cvt_pk_bf16_f32 v82, v86, v87
	v_cvt_pk_bf16_f32 v83, v88, v89
	v_pk_mul_f32 v[74:75], v[74:75], v[168:169] op_sel:[0,1] op_sel_hi:[1,1]
	v_cvt_pk_bf16_f32 v84, v84, v85
	v_cvt_pk_bf16_f32 v85, v90, v91
	global_store_dwordx4 v[98:99], v[82:85], off offset:256 nt
	v_pk_mul_f32 v[76:77], v[76:77], v[168:169] op_sel:[0,1] op_sel_hi:[1,1]
	v_cvt_pk_bf16_f32 v78, v78, v79
	v_cvt_pk_bf16_f32 v79, v80, v81
	v_cvt_pk_bf16_f32 v80, v74, v75
	v_pk_mul_f32 v[72:73], v[72:73], v[168:169] op_sel:[0,1] op_sel_hi:[1,1]
	v_add_u32_e32 v82, 0x84000, v0
	v_mov_b32_e32 v83, v1
	v_lshl_add_u64 v[82:83], v[82:83], 1, s[8:9]
	v_lshl_add_u64 v[82:83], v[82:83], 0, s[22:23]
	v_lshl_add_u64 v[82:83], v[82:83], 0, v[142:143]
	v_cvt_pk_bf16_f32 v81, v76, v77
	global_store_dwordx4 v[82:83], v[78:81], off nt
	v_pk_mul_f32 v[70:71], v[70:71], v[168:169] op_sel:[0,1] op_sel_hi:[1,1]
	v_pk_mul_f32 v[74:75], v[68:69], v[168:169] op_sel:[0,1] op_sel_hi:[1,1]
	v_pk_mul_f32 v[68:69], v[66:67], v[168:169] op_sel:[0,1] op_sel_hi:[1,1]
	v_cvt_pk_bf16_f32 v66, v70, v71
	v_cvt_pk_bf16_f32 v67, v72, v73
	v_pk_mul_f32 v[64:65], v[64:65], v[170:171] op_sel_hi:[1,0]
	v_cvt_pk_bf16_f32 v68, v68, v69
; #define PG8_WAIT_V(n) asm volatile("s_waitcnt vmcnt(" #n ")" ::: "memory")
; #define PG8_BAR __builtin_amdgcn_s_barrier()
;     __device__ __forceinline__ void operator()(const f32x4 (&acc)[2][2][4][2], const Unit& u, int wr, int wc, int fr, int fq) const {
;     ...
; #pragma unroll
;         for (int ai = 0; ai < 2; ++ai)
; #pragma unroll
;             for (int m = 0; m < 4; ++m) {
;                 const unsigned row = (unsigned)(row0 + ai * HALF + m * 16);
; #pragma unroll
;                 for (int bj = 0; bj < 2; ++bj) {
;                     f32x4 v0 = acc[ai][bj][m][0], v1 = acc[ai][bj][m][1];
;                     if constexpr (MODE == EP_IN || MODE == EP_U) { v0 = v0 * rs[ai][m]; v1 = v1 * rs[ai][m]; }
;                     const int ct = bj * HALF + cw;
;     ...
;                         st8nt(WSB(WS_U) + row * 11264 + pn * 256 + ct, v0, v1);
; template <class Epi, class Sched, bool ALIGN_EPI = false, bool SP2 = false>
; __device__ __forceinline__ void gemm_phase(PG8_LAS unsigned char* lds, const Gemm g, const Sched& S, const Epi& E) {
;     ...
;         if constexpr (!Epi::AFTER_DRAIN) { E(acc, cur, wr, wc, fr, fq); S.done(cur); }
;         if (!has_next) break;
; #pragma unroll
;         for (int a = 0; a < 2; ++a)
; #pragma unroll
;             for (int b = 0; b < 2; ++b)
; #pragma unroll
;                 for (int m = 0; m < 4; ++m)
; #pragma unroll
;                     for (int n = 0; n < 2; ++n) acc[a][b][m][n] = (f32x4){0.f, 0.f, 0.f, 0.f};
;         cur = nxt; cA = nA; cB = nB; ++ui;
;         if constexpr (ALIGN_EPI) { if (wr == 1) PG8_BAR; }
;     }
;     PG8_WAIT_V(0);
;     if constexpr (!ALIGN_EPI) { if (wr == 0) PG8_BAR; }
;     PG8_BAR;
	v_cvt_pk_bf16_f32 v69, v74, v75
	global_store_dwordx4 v[82:83], v[66:69], off offset:256 nt
	v_pk_mul_f32 v[62:63], v[62:63], v[170:171] op_sel_hi:[1,0]
	v_pk_mul_f32 v[56:57], v[56:57], v[170:171] op_sel_hi:[1,0]
	v_add_u32_e32 v66, 0x160000, v0
	v_mov_b32_e32 v67, v1
	v_pk_mul_f32 v[68:69], v[60:61], v[170:171] op_sel_hi:[1,0]
	v_pk_mul_f32 v[60:61], v[58:59], v[170:171] op_sel_hi:[1,0]
	v_lshl_add_u64 v[58:59], v[66:67], 1, s[8:9]
	v_lshl_add_u64 v[58:59], v[58:59], 0, s[22:23]
	v_lshl_add_u64 v[66:67], v[58:59], 0, v[142:143]
	v_cvt_pk_bf16_f32 v58, v62, v63
	v_cvt_pk_bf16_f32 v59, v64, v65
	v_cvt_pk_bf16_f32 v60, v60, v61
	v_cvt_pk_bf16_f32 v61, v68, v69
	global_store_dwordx4 v[66:67], v[58:61], off nt
	v_pk_mul_f32 v[54:55], v[54:55], v[170:171] op_sel_hi:[1,0]
	v_pk_mul_f32 v[50:51], v[50:51], v[170:171] op_sel:[0,1] op_sel_hi:[1,1]
	v_pk_mul_f32 v[58:59], v[48:49], v[170:171] op_sel_hi:[1,0]
	v_pk_mul_f32 v[48:49], v[46:47], v[170:171] op_sel_hi:[1,0]
	v_cvt_pk_bf16_f32 v46, v54, v55
	v_cvt_pk_bf16_f32 v47, v56, v57
	v_pk_mul_f32 v[40:41], v[40:41], v[170:171] op_sel:[0,1] op_sel_hi:[1,1]
	v_cvt_pk_bf16_f32 v48, v48, v49
	v_cvt_pk_bf16_f32 v49, v58, v59
	global_store_dwordx4 v[66:67], v[46:49], off offset:256 nt
	v_pk_mul_f32 v[38:39], v[38:39], v[170:171] op_sel:[0,1] op_sel_hi:[1,1]
	v_pk_mul_f32 v[34:35], v[34:35], v[172:173] op_sel_hi:[1,0]
	v_add_u32_e32 v46, 0x18c000, v0
	v_mov_b32_e32 v47, v1
	v_pk_mul_f32 v[48:49], v[52:53], v[170:171] op_sel:[0,1] op_sel_hi:[1,1]
	v_pk_mul_f32 v[52:53], v[44:45], v[170:171] op_sel:[0,1] op_sel_hi:[1,1]
	v_pk_mul_f32 v[44:45], v[42:43], v[170:171] op_sel:[0,1] op_sel_hi:[1,1]
	v_lshl_add_u64 v[42:43], v[46:47], 1, s[8:9]
	v_lshl_add_u64 v[42:43], v[42:43], 0, s[22:23]
	v_lshl_add_u64 v[46:47], v[42:43], 0, v[142:143]
	v_cvt_pk_bf16_f32 v42, v50, v51
	v_cvt_pk_bf16_f32 v43, v48, v49
	v_cvt_pk_bf16_f32 v44, v44, v45
	v_cvt_pk_bf16_f32 v45, v52, v53
	global_store_dwordx4 v[46:47], v[42:45], off nt
	v_pk_mul_f32 v[24:25], v[24:25], v[172:173] op_sel_hi:[1,0]
	v_pk_mul_f32 v[22:23], v[22:23], v[172:173] op_sel_hi:[1,0]
	v_pk_mul_f32 v[42:43], v[32:33], v[170:171] op_sel:[0,1] op_sel_hi:[1,1]
	v_pk_mul_f32 v[32:33], v[30:31], v[170:171] op_sel:[0,1] op_sel_hi:[1,1]
	v_cvt_pk_bf16_f32 v30, v38, v39
	v_cvt_pk_bf16_f32 v31, v40, v41
	v_pk_mul_f32 v[8:9], v[8:9], v[172:173] op_sel:[0,1] op_sel_hi:[1,1]
	v_cvt_pk_bf16_f32 v32, v32, v33
	v_cvt_pk_bf16_f32 v33, v42, v43
	global_store_dwordx4 v[46:47], v[30:33], off offset:256 nt
	v_pk_mul_f32 v[6:7], v[6:7], v[172:173] op_sel:[0,1] op_sel_hi:[1,1]
	s_nop 0
	v_add_u32_e32 v30, 0x1b8000, v0
	v_mov_b32_e32 v31, v1
	v_pk_mul_f32 v[32:33], v[36:37], v[172:173] op_sel_hi:[1,0]
	v_pk_mul_f32 v[36:37], v[28:29], v[172:173] op_sel_hi:[1,0]
	v_pk_mul_f32 v[28:29], v[26:27], v[172:173] op_sel_hi:[1,0]
	v_lshl_add_u64 v[26:27], v[30:31], 1, s[8:9]
	v_lshl_add_u64 v[26:27], v[26:27], 0, s[22:23]
	v_lshl_add_u64 v[30:31], v[26:27], 0, v[142:143]
	v_cvt_pk_bf16_f32 v26, v34, v35
	v_cvt_pk_bf16_f32 v27, v32, v33
	v_cvt_pk_bf16_f32 v28, v28, v29
	v_cvt_pk_bf16_f32 v29, v36, v37
	global_store_dwordx4 v[30:31], v[26:29], off nt
	v_add_u32_e32 v0, 0x1e4000, v0
	s_nop 0
	v_pk_mul_f32 v[26:27], v[16:17], v[172:173] op_sel_hi:[1,0]
	v_pk_mul_f32 v[16:17], v[14:15], v[172:173] op_sel_hi:[1,0]
	v_cvt_pk_bf16_f32 v14, v22, v23
	v_cvt_pk_bf16_f32 v15, v24, v25
	s_nop 0
	v_cvt_pk_bf16_f32 v16, v16, v17
	v_cvt_pk_bf16_f32 v17, v26, v27
	global_store_dwordx4 v[30:31], v[14:17], off offset:256 nt
	s_nop 1
	v_pk_mul_f32 v[16:17], v[18:19], v[172:173] op_sel:[0,1] op_sel_hi:[1,1]
	v_pk_mul_f32 v[18:19], v[12:13], v[172:173] op_sel:[0,1] op_sel_hi:[1,1]
	v_pk_mul_f32 v[12:13], v[10:11], v[172:173] op_sel:[0,1] op_sel_hi:[1,1]
	v_lshl_add_u64 v[10:11], v[0:1], 1, s[8:9]
	v_lshl_add_u64 v[10:11], v[10:11], 0, s[22:23]
	v_pk_mul_f32 v[14:15], v[20:21], v[172:173] op_sel:[0,1] op_sel_hi:[1,1]
	v_lshl_add_u64 v[20:21], v[10:11], 0, v[142:143]
	v_cvt_pk_bf16_f32 v10, v16, v17
	v_cvt_pk_bf16_f32 v11, v14, v15
	v_cvt_pk_bf16_f32 v12, v12, v13
	v_cvt_pk_bf16_f32 v13, v18, v19
	global_store_dwordx4 v[20:21], v[10:13], off nt
	s_mov_b64 s[22:23], -1
	s_nop 0
	v_pk_mul_f32 v[10:11], v[4:5], v[172:173] op_sel:[0,1] op_sel_hi:[1,1]
	v_pk_mul_f32 v[4:5], v[2:3], v[172:173] op_sel:[0,1] op_sel_hi:[1,1]
	v_cvt_pk_bf16_f32 v2, v6, v7
	v_cvt_pk_bf16_f32 v3, v8, v9
	s_nop 0
	v_cvt_pk_bf16_f32 v4, v4, v5
	v_cvt_pk_bf16_f32 v5, v10, v11
	global_store_dwordx4 v[20:21], v[2:5], off offset:256 nt
	s_cbranch_vccnz .LBB0_1730
	s_andn2_b64 vcc, exec, s[6:7]
	s_cbranch_vccnz .LBB0_1729
	s_barrier
	s_branch .LBB0_1729
.LBB0_1740:
	v_mov_b64_e32 v[166:167], 0x9c0
	v_mov_b64_e32 v[168:169], 0x9bf
	v_mov_b64_e32 v[170:171], 0x200
	v_mov_b64_e32 v[172:173], 0x1ff
	s_waitcnt vmcnt(0)
	s_barrier
